# v144 + GEMM unit loops P1/P7/P9/P10: accumulator zeroing (128 v_mov per unit) removed; peeled first K-loop iteration with MFMA C operand = inline 0
# speedup vs baseline: 1.0049x; 1.0036x over previous
.LBB0_114:
	s_ashr_i32 s27, s26, 31
	s_lshl_b64 s[36:37], s[26:27], 20
	s_add_u32 s36, s14, s36
	s_addc_u32 s37, s15, s37
	s_and_b64 s[38:39], s[4:5], exec
	s_cselect_b32 s27, s37, s65
	s_cselect_b32 s82, s36, s64
	s_ashr_i32 s25, s24, 31
	s_lshl_b64 s[38:39], s[24:25], 20
	s_add_u32 s38, s60, s38
	s_addc_u32 s39, s61, s39
	s_and_b64 s[68:69], s[4:5], exec
	s_cselect_b32 s25, s39, s67
	s_cselect_b32 s83, s38, s66
	s_add_u32 s64, s64, 0x80080
	s_addc_u32 s65, s65, 0
	s_add_u32 s84, s66, 0x100
	s_addc_u32 s85, s67, 0
	s_mov_b32 s86, -2
	ds_read_b128 v[144:147], v151
	ds_read_b128 v[154:157], v151 offset:1024
	ds_read_b128 v[158:161], v151 offset:2048
	ds_read_b128 v[162:165], v151 offset:3072
	ds_read_b128 v[166:169], v152
	ds_read_b128 v[170:173], v152 offset:1024
	ds_read_b128 v[174:177], v152 offset:2048
	ds_read_b128 v[178:181], v152 offset:3072
	s_add_u32 s66, s64, 0xfff80080
	s_addc_u32 s67, s65, -1
	s_cmp_eq_u32 s86, 28
	s_cselect_b32 s69, s27, s67
	s_cselect_b32 s68, s82, s66
	s_cselect_b32 s67, s25, s85
	s_cselect_b32 s66, s83, s84
	v_lshl_add_u64 v[210:211], s[64:65], 0, v[136:137]
	s_add_i32 m0, s41, 0xc000
	ds_read_b128 v[182:185], v153
	ds_read_b128 v[186:189], v153 offset:1024
	ds_read_b128 v[190:193], v153 offset:2048
	ds_read_b128 v[194:197], v153 offset:3072
	ds_read_b128 v[198:201], v153 offset:4096
	ds_read_b128 v[202:205], v153 offset:5120
	ds_read_b128 v[206:209], v153 offset:6144
	ds_read_b128 v[214:217], v153 offset:7168
	global_load_lds_dwordx4 v[210:211], off
	v_lshl_add_u64 v[210:211], s[64:65], 0, v[138:139]
	s_add_i32 m0, s41, 0xe000
	s_nop 0
	global_load_lds_dwordx4 v[210:211], off
	s_waitcnt vmcnt(8)
	s_waitcnt lgkmcnt(0)
	s_barrier
	s_setprio 1
	s_waitcnt lgkmcnt(0)
	v_mfma_f32_16x16x32_bf16 v[124:127], v[144:147], v[182:185], 0
	v_mfma_f32_16x16x32_bf16 v[120:123], v[158:161], v[182:185], 0
	v_mfma_f32_16x16x32_bf16 v[116:119], v[144:147], v[190:193], 0
	v_mfma_f32_16x16x32_bf16 v[112:115], v[158:161], v[190:193], 0
	v_mfma_f32_16x16x32_bf16 v[100:103], v[144:147], v[198:201], 0
	v_mfma_f32_16x16x32_bf16 v[96:99], v[158:161], v[198:201], 0
	v_mfma_f32_16x16x32_bf16 v[76:79], v[144:147], v[206:209], 0
	v_mfma_f32_16x16x32_bf16 v[72:75], v[158:161], v[206:209], 0
	v_mfma_f32_16x16x32_bf16 v[124:127], v[154:157], v[186:189], v[124:127]
	v_mfma_f32_16x16x32_bf16 v[120:123], v[162:165], v[186:189], v[120:123]
	v_mfma_f32_16x16x32_bf16 v[116:119], v[154:157], v[194:197], v[116:119]
	v_mfma_f32_16x16x32_bf16 v[112:115], v[162:165], v[194:197], v[112:115]
	v_mfma_f32_16x16x32_bf16 v[100:103], v[154:157], v[202:205], v[100:103]
	v_mfma_f32_16x16x32_bf16 v[96:99], v[162:165], v[202:205], v[96:99]
	v_mfma_f32_16x16x32_bf16 v[76:79], v[154:157], v[214:217], v[76:79]
	v_mfma_f32_16x16x32_bf16 v[72:75], v[162:165], v[214:217], v[72:75]
	s_setprio 0
	s_setprio 1
	v_mfma_f32_16x16x32_bf16 v[108:111], v[166:169], v[182:185], 0
	v_mfma_f32_16x16x32_bf16 v[104:107], v[174:177], v[182:185], 0
	v_mfma_f32_16x16x32_bf16 v[92:95], v[166:169], v[190:193], 0
	v_mfma_f32_16x16x32_bf16 v[88:91], v[174:177], v[190:193], 0
	v_mfma_f32_16x16x32_bf16 v[84:87], v[166:169], v[198:201], 0
	v_mfma_f32_16x16x32_bf16 v[80:83], v[174:177], v[198:201], 0
	v_mfma_f32_16x16x32_bf16 v[68:71], v[166:169], v[206:209], 0
	v_mfma_f32_16x16x32_bf16 v[64:67], v[174:177], v[206:209], 0
	v_mfma_f32_16x16x32_bf16 v[108:111], v[170:173], v[186:189], v[108:111]
	v_mfma_f32_16x16x32_bf16 v[104:107], v[178:181], v[186:189], v[104:107]
	v_mfma_f32_16x16x32_bf16 v[92:95], v[170:173], v[194:197], v[92:95]
	v_mfma_f32_16x16x32_bf16 v[88:91], v[178:181], v[194:197], v[88:91]
	v_mfma_f32_16x16x32_bf16 v[84:87], v[170:173], v[202:205], v[84:87]
	v_mfma_f32_16x16x32_bf16 v[80:83], v[178:181], v[202:205], v[80:83]
	v_mfma_f32_16x16x32_bf16 v[68:71], v[170:173], v[214:217], v[68:71]
	v_mfma_f32_16x16x32_bf16 v[64:67], v[178:181], v[214:217], v[64:67]
	s_setprio 0
	s_barrier
	s_add_i32 s87, s78, s3
	v_lshl_add_u64 v[210:211], s[66:67], 0, v[132:133]
	s_mov_b32 m0, s87
	ds_read_b128 v[182:185], v153 offset:16384
	ds_read_b128 v[186:189], v153 offset:17408
	ds_read_b128 v[190:193], v153 offset:18432
	ds_read_b128 v[194:197], v153 offset:19456
	ds_read_b128 v[198:201], v153 offset:20480
	ds_read_b128 v[202:205], v153 offset:21504
	ds_read_b128 v[206:209], v153 offset:22528
	ds_read_b128 v[214:217], v153 offset:23552
	global_load_lds_dwordx4 v[210:211], off
	s_add_i32 m0, s87, 0x2000
	s_add_u32 s88, s66, 0x80000
	v_lshl_add_u64 v[218:219], s[66:67], 0, v[128:129]
	s_addc_u32 s89, s67, 0
	s_add_i32 s87, s79, s3
	global_load_lds_dwordx4 v[218:219], off
	v_lshl_add_u64 v[220:221], s[88:89], 0, v[132:133]
	s_mov_b32 m0, s87
	v_lshl_add_u64 v[222:223], s[68:69], 0, v[130:131]
	global_load_lds_dwordx4 v[220:221], off
	v_lshl_add_u64 v[220:221], s[88:89], 0, v[128:129]
	s_add_i32 m0, s87, 0x2000
	s_nop 0
	global_load_lds_dwordx4 v[220:221], off
	v_lshl_add_u64 v[220:221], s[68:69], 0, v[134:135]
	s_mov_b32 m0, s41
	s_nop 0
	global_load_lds_dwordx4 v[220:221], off
	s_mov_b32 m0, s70
	s_nop 0
	global_load_lds_dwordx4 v[222:223], off
	s_waitcnt vmcnt(8)
	s_waitcnt lgkmcnt(0)
	s_barrier
	s_setprio 1
	s_waitcnt lgkmcnt(0)
	v_mfma_f32_16x16x32_bf16 v[60:63], v[144:147], v[182:185], 0
	v_mfma_f32_16x16x32_bf16 v[56:59], v[158:161], v[182:185], 0
	v_mfma_f32_16x16x32_bf16 v[52:55], v[144:147], v[190:193], 0
	v_mfma_f32_16x16x32_bf16 v[44:47], v[158:161], v[190:193], 0
	v_mfma_f32_16x16x32_bf16 v[36:39], v[144:147], v[198:201], 0
	v_mfma_f32_16x16x32_bf16 v[28:31], v[158:161], v[198:201], 0
	v_mfma_f32_16x16x32_bf16 v[20:23], v[144:147], v[206:209], 0
	v_mfma_f32_16x16x32_bf16 v[12:15], v[158:161], v[206:209], 0
	v_mfma_f32_16x16x32_bf16 v[60:63], v[154:157], v[186:189], v[60:63]
	v_mfma_f32_16x16x32_bf16 v[56:59], v[162:165], v[186:189], v[56:59]
	v_mfma_f32_16x16x32_bf16 v[52:55], v[154:157], v[194:197], v[52:55]
	v_mfma_f32_16x16x32_bf16 v[44:47], v[162:165], v[194:197], v[44:47]
	v_mfma_f32_16x16x32_bf16 v[36:39], v[154:157], v[202:205], v[36:39]
	v_mfma_f32_16x16x32_bf16 v[28:31], v[162:165], v[202:205], v[28:31]
	v_mfma_f32_16x16x32_bf16 v[20:23], v[154:157], v[214:217], v[20:23]
	v_mfma_f32_16x16x32_bf16 v[12:15], v[162:165], v[214:217], v[12:15]
	s_setprio 0
	s_setprio 1
	v_mfma_f32_16x16x32_bf16 v[48:51], v[166:169], v[182:185], 0
	v_mfma_f32_16x16x32_bf16 v[40:43], v[174:177], v[182:185], 0
	v_mfma_f32_16x16x32_bf16 v[32:35], v[166:169], v[190:193], 0
	v_mfma_f32_16x16x32_bf16 v[24:27], v[174:177], v[190:193], 0
	v_mfma_f32_16x16x32_bf16 v[16:19], v[166:169], v[198:201], 0
	v_mfma_f32_16x16x32_bf16 v[8:11], v[174:177], v[198:201], 0
	v_mfma_f32_16x16x32_bf16 v[4:7], v[166:169], v[206:209], 0
	v_mfma_f32_16x16x32_bf16 v[0:3], v[174:177], v[206:209], 0
	v_mfma_f32_16x16x32_bf16 v[48:51], v[170:173], v[186:189], v[48:51]
	v_mfma_f32_16x16x32_bf16 v[40:43], v[178:181], v[186:189], v[40:43]
	v_mfma_f32_16x16x32_bf16 v[32:35], v[170:173], v[194:197], v[32:35]
	v_mfma_f32_16x16x32_bf16 v[24:27], v[178:181], v[194:197], v[24:27]
	v_mfma_f32_16x16x32_bf16 v[16:19], v[170:173], v[202:205], v[16:19]
	v_mfma_f32_16x16x32_bf16 v[8:11], v[178:181], v[202:205], v[8:11]
	v_mfma_f32_16x16x32_bf16 v[4:7], v[170:173], v[214:217], v[4:7]
	v_mfma_f32_16x16x32_bf16 v[0:3], v[178:181], v[214:217], v[0:3]
	s_setprio 0
	s_barrier
	s_add_i32 s87, 0, 0x18000
	s_add_i32 s88, 0, 0x1c000
	v_add_u32_e32 v162, s87, v149
	v_add_u32_e32 v178, s88, v149
	ds_read_b128 v[144:147], v162
	ds_read_b128 v[154:157], v162 offset:1024
	ds_read_b128 v[158:161], v162 offset:2048
	ds_read_b128 v[162:165], v162 offset:3072
	ds_read_b128 v[166:169], v178
	ds_read_b128 v[170:173], v178 offset:1024
	ds_read_b128 v[174:177], v178 offset:2048
	ds_read_b128 v[178:181], v178 offset:3072
	s_add_u32 s68, s68, 0x80000
	s_addc_u32 s69, s69, 0
	s_mov_b32 m0, s71
	v_lshl_add_u64 v[224:225], s[68:69], 0, v[134:135]
	ds_read_b128 v[182:185], v153 offset:32768
	ds_read_b128 v[186:189], v153 offset:33792
	ds_read_b128 v[190:193], v153 offset:34816
	ds_read_b128 v[194:197], v153 offset:35840
	ds_read_b128 v[198:201], v153 offset:36864
	ds_read_b128 v[202:205], v153 offset:37888
	ds_read_b128 v[206:209], v153 offset:38912
	ds_read_b128 v[214:217], v153 offset:39936
	global_load_lds_dwordx4 v[224:225], off
	v_lshl_add_u64 v[224:225], s[68:69], 0, v[130:131]
	s_mov_b32 m0, s72
	s_nop 0
	global_load_lds_dwordx4 v[224:225], off
	s_waitcnt vmcnt(8)
	s_waitcnt lgkmcnt(0)
	s_barrier
	s_setprio 1
	s_waitcnt lgkmcnt(0)
	v_mfma_f32_16x16x32_bf16 v[124:127], v[144:147], v[182:185], v[124:127]
	v_mfma_f32_16x16x32_bf16 v[120:123], v[158:161], v[182:185], v[120:123]
	v_mfma_f32_16x16x32_bf16 v[116:119], v[144:147], v[190:193], v[116:119]
	v_mfma_f32_16x16x32_bf16 v[112:115], v[158:161], v[190:193], v[112:115]
	v_mfma_f32_16x16x32_bf16 v[100:103], v[144:147], v[198:201], v[100:103]
	v_mfma_f32_16x16x32_bf16 v[96:99], v[158:161], v[198:201], v[96:99]
	v_mfma_f32_16x16x32_bf16 v[76:79], v[144:147], v[206:209], v[76:79]
	v_mfma_f32_16x16x32_bf16 v[72:75], v[158:161], v[206:209], v[72:75]
	v_mfma_f32_16x16x32_bf16 v[124:127], v[154:157], v[186:189], v[124:127]
	v_mfma_f32_16x16x32_bf16 v[120:123], v[162:165], v[186:189], v[120:123]
	v_mfma_f32_16x16x32_bf16 v[116:119], v[154:157], v[194:197], v[116:119]
	v_mfma_f32_16x16x32_bf16 v[112:115], v[162:165], v[194:197], v[112:115]
	v_mfma_f32_16x16x32_bf16 v[100:103], v[154:157], v[202:205], v[100:103]
	v_mfma_f32_16x16x32_bf16 v[96:99], v[162:165], v[202:205], v[96:99]
	v_mfma_f32_16x16x32_bf16 v[76:79], v[154:157], v[214:217], v[76:79]
	v_mfma_f32_16x16x32_bf16 v[72:75], v[162:165], v[214:217], v[72:75]
	s_setprio 0
	s_setprio 1
	v_mfma_f32_16x16x32_bf16 v[108:111], v[166:169], v[182:185], v[108:111]
	v_mfma_f32_16x16x32_bf16 v[104:107], v[174:177], v[182:185], v[104:107]
	v_mfma_f32_16x16x32_bf16 v[92:95], v[166:169], v[190:193], v[92:95]
	v_mfma_f32_16x16x32_bf16 v[88:91], v[174:177], v[190:193], v[88:91]
	v_mfma_f32_16x16x32_bf16 v[84:87], v[166:169], v[198:201], v[84:87]
	v_mfma_f32_16x16x32_bf16 v[80:83], v[174:177], v[198:201], v[80:83]
	v_mfma_f32_16x16x32_bf16 v[68:71], v[166:169], v[206:209], v[68:71]
	v_mfma_f32_16x16x32_bf16 v[64:67], v[174:177], v[206:209], v[64:67]
	v_mfma_f32_16x16x32_bf16 v[108:111], v[170:173], v[186:189], v[108:111]
	v_mfma_f32_16x16x32_bf16 v[104:107], v[178:181], v[186:189], v[104:107]
	v_mfma_f32_16x16x32_bf16 v[92:95], v[170:173], v[194:197], v[92:95]
	v_mfma_f32_16x16x32_bf16 v[88:91], v[178:181], v[194:197], v[88:91]
	v_mfma_f32_16x16x32_bf16 v[84:87], v[170:173], v[202:205], v[84:87]
	v_mfma_f32_16x16x32_bf16 v[80:83], v[178:181], v[202:205], v[80:83]
	v_mfma_f32_16x16x32_bf16 v[68:71], v[170:173], v[214:217], v[68:71]
	v_mfma_f32_16x16x32_bf16 v[64:67], v[178:181], v[214:217], v[64:67]
	s_setprio 0
	s_barrier
	s_add_i32 s68, s87, s3
	v_lshl_add_u64 v[210:211], v[210:211], 0, s[20:21]
	s_mov_b32 m0, s68
	ds_read_b128 v[182:185], v153 offset:49152
	ds_read_b128 v[186:189], v153 offset:50176
	ds_read_b128 v[190:193], v153 offset:51200
	ds_read_b128 v[194:197], v153 offset:52224
	ds_read_b128 v[198:201], v153 offset:53248
	ds_read_b128 v[202:205], v153 offset:54272
	ds_read_b128 v[206:209], v153 offset:55296
	ds_read_b128 v[214:217], v153 offset:56320
	global_load_lds_dwordx4 v[210:211], off
	s_add_i32 m0, s68, 0x2000
	s_add_u32 s66, s66, 0x80080
	v_lshl_add_u64 v[210:211], v[218:219], 0, s[20:21]
	s_addc_u32 s67, s67, 0
	s_add_i32 s68, s88, s3
	global_load_lds_dwordx4 v[210:211], off
	v_lshl_add_u64 v[210:211], s[66:67], 0, v[132:133]
	s_mov_b32 m0, s68
	s_nop 0
	global_load_lds_dwordx4 v[210:211], off
	v_lshl_add_u64 v[210:211], s[66:67], 0, v[128:129]
	s_add_i32 m0, s68, 0x2000
	s_nop 0
	global_load_lds_dwordx4 v[210:211], off
	v_lshl_add_u64 v[210:211], v[220:221], 0, s[20:21]
	s_mov_b32 m0, s74
	s_nop 0
	global_load_lds_dwordx4 v[210:211], off
	v_lshl_add_u64 v[210:211], v[222:223], 0, s[20:21]
	s_mov_b32 m0, s75
	s_nop 0
	global_load_lds_dwordx4 v[210:211], off
	s_waitcnt vmcnt(8)
	s_waitcnt lgkmcnt(0)
	s_barrier
	s_setprio 1
	s_waitcnt lgkmcnt(0)
	v_mfma_f32_16x16x32_bf16 v[60:63], v[144:147], v[182:185], v[60:63]
	v_mfma_f32_16x16x32_bf16 v[56:59], v[158:161], v[182:185], v[56:59]
	v_mfma_f32_16x16x32_bf16 v[52:55], v[144:147], v[190:193], v[52:55]
	v_mfma_f32_16x16x32_bf16 v[44:47], v[158:161], v[190:193], v[44:47]
	v_mfma_f32_16x16x32_bf16 v[36:39], v[144:147], v[198:201], v[36:39]
	v_mfma_f32_16x16x32_bf16 v[28:31], v[158:161], v[198:201], v[28:31]
	v_mfma_f32_16x16x32_bf16 v[20:23], v[144:147], v[206:209], v[20:23]
	v_mfma_f32_16x16x32_bf16 v[12:15], v[158:161], v[206:209], v[12:15]
	v_mfma_f32_16x16x32_bf16 v[60:63], v[154:157], v[186:189], v[60:63]
	v_mfma_f32_16x16x32_bf16 v[56:59], v[162:165], v[186:189], v[56:59]
	v_mfma_f32_16x16x32_bf16 v[52:55], v[154:157], v[194:197], v[52:55]
	v_mfma_f32_16x16x32_bf16 v[44:47], v[162:165], v[194:197], v[44:47]
	v_mfma_f32_16x16x32_bf16 v[36:39], v[154:157], v[202:205], v[36:39]
	v_mfma_f32_16x16x32_bf16 v[28:31], v[162:165], v[202:205], v[28:31]
	v_mfma_f32_16x16x32_bf16 v[20:23], v[154:157], v[214:217], v[20:23]
	v_mfma_f32_16x16x32_bf16 v[12:15], v[162:165], v[214:217], v[12:15]
	s_setprio 0
	s_setprio 1
	v_mfma_f32_16x16x32_bf16 v[48:51], v[166:169], v[182:185], v[48:51]
	v_mfma_f32_16x16x32_bf16 v[40:43], v[174:177], v[182:185], v[40:43]
	v_mfma_f32_16x16x32_bf16 v[32:35], v[166:169], v[190:193], v[32:35]
	v_mfma_f32_16x16x32_bf16 v[24:27], v[174:177], v[190:193], v[24:27]
	v_mfma_f32_16x16x32_bf16 v[16:19], v[166:169], v[198:201], v[16:19]
	v_mfma_f32_16x16x32_bf16 v[8:11], v[174:177], v[198:201], v[8:11]
	v_mfma_f32_16x16x32_bf16 v[4:7], v[166:169], v[206:209], v[4:7]
	v_mfma_f32_16x16x32_bf16 v[0:3], v[174:177], v[206:209], v[0:3]
	v_mfma_f32_16x16x32_bf16 v[48:51], v[170:173], v[186:189], v[48:51]
	v_mfma_f32_16x16x32_bf16 v[40:43], v[178:181], v[186:189], v[40:43]
	v_mfma_f32_16x16x32_bf16 v[32:35], v[170:173], v[194:197], v[32:35]
	v_mfma_f32_16x16x32_bf16 v[24:27], v[178:181], v[194:197], v[24:27]
	v_mfma_f32_16x16x32_bf16 v[16:19], v[170:173], v[202:205], v[16:19]
	v_mfma_f32_16x16x32_bf16 v[8:11], v[178:181], v[202:205], v[8:11]
	v_mfma_f32_16x16x32_bf16 v[4:7], v[170:173], v[214:217], v[4:7]
	v_mfma_f32_16x16x32_bf16 v[0:3], v[178:181], v[214:217], v[0:3]
	s_setprio 0
	s_barrier
	s_add_i32 s86, s86, 2
	s_add_u32 s64, s64, 0x100
	s_addc_u32 s65, s65, 0
	s_add_u32 s84, s84, 0x100
	s_addc_u32 s85, s85, 0
	s_cmp_gt_u32 s86, 29

.LBB0_458:
	s_ashr_i32 s25, s24, 31
	v_cmp_lt_i64_e32 vcc, s[26:27], v[154:155]
	s_lshl_b64 s[26:27], s[24:25], 20
	s_add_u32 s26, s20, s26
	s_addc_u32 s27, s21, s27
	s_and_b64 s[34:35], vcc, exec
	s_cselect_b32 s25, s27, s39
	s_cselect_b32 s37, s26, s38
	s_ashr_i32 s23, s22, 31
	s_lshl_b64 s[34:35], s[22:23], 20
	s_add_u32 s34, s44, s34
	s_addc_u32 s35, s45, s35
	s_and_b64 s[42:43], vcc, exec
	s_cselect_b32 s23, s35, s41
	s_cselect_b32 s63, s34, s40
	s_add_u32 s38, s38, 0x80080
	s_addc_u32 s39, s39, 0
	s_add_u32 s64, s40, 0x100
	s_addc_u32 s65, s41, 0
	s_mov_b32 s67, -2
	s_waitcnt lgkmcnt(0)
	ds_read_b128 v[128:131], v171
	ds_read_b128 v[132:135], v171 offset:1024
	ds_read_b128 v[136:139], v171 offset:2048
	ds_read_b128 v[158:161], v171 offset:3072
	ds_read_b128 v[162:165], v177
	ds_read_b128 v[180:183], v177 offset:1024
	ds_read_b128 v[184:187], v177 offset:2048
	ds_read_b128 v[188:191], v177 offset:3072
	s_add_u32 s40, s38, 0xfff80080
	s_addc_u32 s41, s39, -1
	s_cmp_eq_u32 s67, 28
	s_cselect_b32 s43, s25, s41
	s_cselect_b32 s42, s37, s40
	s_cselect_b32 s41, s23, s65
	s_cselect_b32 s40, s63, s64
	v_lshl_add_u64 v[226:227], s[38:39], 0, v[150:151]
	s_add_i32 m0, s47, 0xc000
	ds_read_b128 v[192:195], v178
	ds_read_b128 v[196:199], v178 offset:1024
	ds_read_b128 v[200:203], v178 offset:2048
	ds_read_b128 v[204:207], v178 offset:3072
	ds_read_b128 v[208:211], v178 offset:4096
	ds_read_b128 v[214:217], v178 offset:5120
	ds_read_b128 v[218:221], v178 offset:6144
	ds_read_b128 v[222:225], v178 offset:7168
	global_load_lds_dwordx4 v[226:227], off
	v_lshl_add_u64 v[226:227], s[38:39], 0, v[152:153]
	s_add_i32 m0, s47, 0xe000
	s_nop 0
	global_load_lds_dwordx4 v[226:227], off
	s_waitcnt vmcnt(8)
	s_waitcnt lgkmcnt(0)
	s_barrier
	s_setprio 1
	s_waitcnt lgkmcnt(0)
	v_mfma_f32_16x16x32_bf16 v[124:127], v[128:131], v[192:195], 0
	v_mfma_f32_16x16x32_bf16 v[120:123], v[136:139], v[192:195], 0
	v_mfma_f32_16x16x32_bf16 v[108:111], v[128:131], v[200:203], 0
	v_mfma_f32_16x16x32_bf16 v[104:107], v[136:139], v[200:203], 0
	v_mfma_f32_16x16x32_bf16 v[92:95], v[128:131], v[208:211], 0
	v_mfma_f32_16x16x32_bf16 v[88:91], v[136:139], v[208:211], 0
	v_mfma_f32_16x16x32_bf16 v[76:79], v[128:131], v[218:221], 0
	v_mfma_f32_16x16x32_bf16 v[72:75], v[136:139], v[218:221], 0
	v_mfma_f32_16x16x32_bf16 v[124:127], v[132:135], v[196:199], v[124:127]
	v_mfma_f32_16x16x32_bf16 v[120:123], v[158:161], v[196:199], v[120:123]
	v_mfma_f32_16x16x32_bf16 v[108:111], v[132:135], v[204:207], v[108:111]
	v_mfma_f32_16x16x32_bf16 v[104:107], v[158:161], v[204:207], v[104:107]
	v_mfma_f32_16x16x32_bf16 v[92:95], v[132:135], v[214:217], v[92:95]
	v_mfma_f32_16x16x32_bf16 v[88:91], v[158:161], v[214:217], v[88:91]
	v_mfma_f32_16x16x32_bf16 v[76:79], v[132:135], v[222:225], v[76:79]
	v_mfma_f32_16x16x32_bf16 v[72:75], v[158:161], v[222:225], v[72:75]
	s_setprio 0
	s_setprio 1
	v_mfma_f32_16x16x32_bf16 v[116:119], v[162:165], v[192:195], 0
	v_mfma_f32_16x16x32_bf16 v[112:115], v[184:187], v[192:195], 0
	v_mfma_f32_16x16x32_bf16 v[100:103], v[162:165], v[200:203], 0
	v_mfma_f32_16x16x32_bf16 v[96:99], v[184:187], v[200:203], 0
	v_mfma_f32_16x16x32_bf16 v[84:87], v[162:165], v[208:211], 0
	v_mfma_f32_16x16x32_bf16 v[80:83], v[184:187], v[208:211], 0
	v_mfma_f32_16x16x32_bf16 v[68:71], v[162:165], v[218:221], 0
	v_mfma_f32_16x16x32_bf16 v[64:67], v[184:187], v[218:221], 0
	v_mfma_f32_16x16x32_bf16 v[116:119], v[180:183], v[196:199], v[116:119]
	v_mfma_f32_16x16x32_bf16 v[112:115], v[188:191], v[196:199], v[112:115]
	v_mfma_f32_16x16x32_bf16 v[100:103], v[180:183], v[204:207], v[100:103]
	v_mfma_f32_16x16x32_bf16 v[96:99], v[188:191], v[204:207], v[96:99]
	v_mfma_f32_16x16x32_bf16 v[84:87], v[180:183], v[214:217], v[84:87]
	v_mfma_f32_16x16x32_bf16 v[80:83], v[188:191], v[214:217], v[80:83]
	v_mfma_f32_16x16x32_bf16 v[68:71], v[180:183], v[222:225], v[68:71]
	v_mfma_f32_16x16x32_bf16 v[64:67], v[188:191], v[222:225], v[64:67]
	s_setprio 0
	s_barrier
	s_add_i32 s68, s56, s46
	v_lshl_add_u64 v[226:227], s[40:41], 0, v[142:143]
	s_mov_b32 m0, s68
	ds_read_b128 v[192:195], v178 offset:16384
	ds_read_b128 v[196:199], v178 offset:17408
	ds_read_b128 v[200:203], v178 offset:18432
	ds_read_b128 v[204:207], v178 offset:19456
	ds_read_b128 v[208:211], v178 offset:20480
	ds_read_b128 v[214:217], v178 offset:21504
	ds_read_b128 v[218:221], v178 offset:22528
	ds_read_b128 v[222:225], v178 offset:23552
	global_load_lds_dwordx4 v[226:227], off
	s_add_i32 m0, s68, 0x2000
	s_add_u32 s68, s40, 0x80000
	v_lshl_add_u64 v[228:229], s[40:41], 0, v[146:147]
	s_addc_u32 s69, s41, 0
	s_add_i32 s70, s57, s46
	global_load_lds_dwordx4 v[228:229], off
	v_lshl_add_u64 v[230:231], s[68:69], 0, v[142:143]
	s_mov_b32 m0, s70
	v_lshl_add_u64 v[232:233], s[42:43], 0, v[144:145]
	global_load_lds_dwordx4 v[230:231], off
	v_lshl_add_u64 v[230:231], s[68:69], 0, v[146:147]
	s_add_i32 m0, s70, 0x2000
	s_nop 0
	global_load_lds_dwordx4 v[230:231], off
	v_lshl_add_u64 v[230:231], s[42:43], 0, v[140:141]
	s_mov_b32 m0, s47
	s_nop 0
	global_load_lds_dwordx4 v[230:231], off
	s_mov_b32 m0, s48
	s_nop 0
	global_load_lds_dwordx4 v[232:233], off
	s_waitcnt vmcnt(8)
	s_waitcnt lgkmcnt(0)
	s_barrier
	s_setprio 1
	s_waitcnt lgkmcnt(0)
	v_mfma_f32_16x16x32_bf16 v[60:63], v[128:131], v[192:195], 0
	v_mfma_f32_16x16x32_bf16 v[56:59], v[136:139], v[192:195], 0
	v_mfma_f32_16x16x32_bf16 v[44:47], v[128:131], v[200:203], 0
	v_mfma_f32_16x16x32_bf16 v[40:43], v[136:139], v[200:203], 0
	v_mfma_f32_16x16x32_bf16 v[28:31], v[128:131], v[208:211], 0
	v_mfma_f32_16x16x32_bf16 v[24:27], v[136:139], v[208:211], 0
	v_mfma_f32_16x16x32_bf16 v[12:15], v[128:131], v[218:221], 0
	v_mfma_f32_16x16x32_bf16 v[8:11], v[136:139], v[218:221], 0
	v_mfma_f32_16x16x32_bf16 v[60:63], v[132:135], v[196:199], v[60:63]
	v_mfma_f32_16x16x32_bf16 v[56:59], v[158:161], v[196:199], v[56:59]
	v_mfma_f32_16x16x32_bf16 v[44:47], v[132:135], v[204:207], v[44:47]
	v_mfma_f32_16x16x32_bf16 v[40:43], v[158:161], v[204:207], v[40:43]
	v_mfma_f32_16x16x32_bf16 v[28:31], v[132:135], v[214:217], v[28:31]
	v_mfma_f32_16x16x32_bf16 v[24:27], v[158:161], v[214:217], v[24:27]
	v_mfma_f32_16x16x32_bf16 v[12:15], v[132:135], v[222:225], v[12:15]
	v_mfma_f32_16x16x32_bf16 v[8:11], v[158:161], v[222:225], v[8:11]
	s_setprio 0
	s_setprio 1
	v_mfma_f32_16x16x32_bf16 v[52:55], v[162:165], v[192:195], 0
	v_mfma_f32_16x16x32_bf16 v[48:51], v[184:187], v[192:195], 0
	v_mfma_f32_16x16x32_bf16 v[36:39], v[162:165], v[200:203], 0
	v_mfma_f32_16x16x32_bf16 v[32:35], v[184:187], v[200:203], 0
	v_mfma_f32_16x16x32_bf16 v[20:23], v[162:165], v[208:211], 0
	v_mfma_f32_16x16x32_bf16 v[16:19], v[184:187], v[208:211], 0
	v_mfma_f32_16x16x32_bf16 v[4:7], v[162:165], v[218:221], 0
	v_mfma_f32_16x16x32_bf16 v[0:3], v[184:187], v[218:221], 0
	v_mfma_f32_16x16x32_bf16 v[52:55], v[180:183], v[196:199], v[52:55]
	v_mfma_f32_16x16x32_bf16 v[48:51], v[188:191], v[196:199], v[48:51]
	v_mfma_f32_16x16x32_bf16 v[36:39], v[180:183], v[204:207], v[36:39]
	v_mfma_f32_16x16x32_bf16 v[32:35], v[188:191], v[204:207], v[32:35]
	v_mfma_f32_16x16x32_bf16 v[20:23], v[180:183], v[214:217], v[20:23]
	v_mfma_f32_16x16x32_bf16 v[16:19], v[188:191], v[214:217], v[16:19]
	v_mfma_f32_16x16x32_bf16 v[4:7], v[180:183], v[222:225], v[4:7]
	v_mfma_f32_16x16x32_bf16 v[0:3], v[188:191], v[222:225], v[0:3]
	s_setprio 0
	s_barrier
	s_add_i32 s68, 0, 0x18000
	s_add_i32 s69, 0, 0x1c000
	v_add_u32_e32 v158, s68, v167
	v_add_u32_e32 v188, s69, v167
	ds_read_b128 v[128:131], v158
	ds_read_b128 v[132:135], v158 offset:1024
	ds_read_b128 v[136:139], v158 offset:2048
	ds_read_b128 v[158:161], v158 offset:3072
	ds_read_b128 v[162:165], v188
	ds_read_b128 v[180:183], v188 offset:1024
	ds_read_b128 v[184:187], v188 offset:2048
	ds_read_b128 v[188:191], v188 offset:3072
	s_add_u32 s42, s42, 0x80000
	s_addc_u32 s43, s43, 0
	s_mov_b32 m0, s49
	v_lshl_add_u64 v[234:235], s[42:43], 0, v[140:141]
	ds_read_b128 v[192:195], v178 offset:32768
	ds_read_b128 v[196:199], v178 offset:33792
	ds_read_b128 v[200:203], v178 offset:34816
	ds_read_b128 v[204:207], v178 offset:35840
	ds_read_b128 v[208:211], v178 offset:36864
	ds_read_b128 v[214:217], v178 offset:37888
	ds_read_b128 v[218:221], v178 offset:38912
	ds_read_b128 v[222:225], v178 offset:39936
	global_load_lds_dwordx4 v[234:235], off
	v_lshl_add_u64 v[234:235], s[42:43], 0, v[144:145]
	s_mov_b32 m0, s50
	s_nop 0
	global_load_lds_dwordx4 v[234:235], off
	s_waitcnt vmcnt(8)
	s_waitcnt lgkmcnt(0)
	s_barrier
	s_setprio 1
	s_waitcnt lgkmcnt(0)
	v_mfma_f32_16x16x32_bf16 v[124:127], v[128:131], v[192:195], v[124:127]
	v_mfma_f32_16x16x32_bf16 v[120:123], v[136:139], v[192:195], v[120:123]
	v_mfma_f32_16x16x32_bf16 v[108:111], v[128:131], v[200:203], v[108:111]
	v_mfma_f32_16x16x32_bf16 v[104:107], v[136:139], v[200:203], v[104:107]
	v_mfma_f32_16x16x32_bf16 v[92:95], v[128:131], v[208:211], v[92:95]
	v_mfma_f32_16x16x32_bf16 v[88:91], v[136:139], v[208:211], v[88:91]
	v_mfma_f32_16x16x32_bf16 v[76:79], v[128:131], v[218:221], v[76:79]
	v_mfma_f32_16x16x32_bf16 v[72:75], v[136:139], v[218:221], v[72:75]
	v_mfma_f32_16x16x32_bf16 v[124:127], v[132:135], v[196:199], v[124:127]
	v_mfma_f32_16x16x32_bf16 v[120:123], v[158:161], v[196:199], v[120:123]
	v_mfma_f32_16x16x32_bf16 v[108:111], v[132:135], v[204:207], v[108:111]
	v_mfma_f32_16x16x32_bf16 v[104:107], v[158:161], v[204:207], v[104:107]
	v_mfma_f32_16x16x32_bf16 v[92:95], v[132:135], v[214:217], v[92:95]
	v_mfma_f32_16x16x32_bf16 v[88:91], v[158:161], v[214:217], v[88:91]
	v_mfma_f32_16x16x32_bf16 v[76:79], v[132:135], v[222:225], v[76:79]
	v_mfma_f32_16x16x32_bf16 v[72:75], v[158:161], v[222:225], v[72:75]
	s_setprio 0
	s_setprio 1
	v_mfma_f32_16x16x32_bf16 v[116:119], v[162:165], v[192:195], v[116:119]
	v_mfma_f32_16x16x32_bf16 v[112:115], v[184:187], v[192:195], v[112:115]
	v_mfma_f32_16x16x32_bf16 v[100:103], v[162:165], v[200:203], v[100:103]
	v_mfma_f32_16x16x32_bf16 v[96:99], v[184:187], v[200:203], v[96:99]
	v_mfma_f32_16x16x32_bf16 v[84:87], v[162:165], v[208:211], v[84:87]
	v_mfma_f32_16x16x32_bf16 v[80:83], v[184:187], v[208:211], v[80:83]
	v_mfma_f32_16x16x32_bf16 v[68:71], v[162:165], v[218:221], v[68:71]
	v_mfma_f32_16x16x32_bf16 v[64:67], v[184:187], v[218:221], v[64:67]
	v_mfma_f32_16x16x32_bf16 v[116:119], v[180:183], v[196:199], v[116:119]
	v_mfma_f32_16x16x32_bf16 v[112:115], v[188:191], v[196:199], v[112:115]
	v_mfma_f32_16x16x32_bf16 v[100:103], v[180:183], v[204:207], v[100:103]
	v_mfma_f32_16x16x32_bf16 v[96:99], v[188:191], v[204:207], v[96:99]
	v_mfma_f32_16x16x32_bf16 v[84:87], v[180:183], v[214:217], v[84:87]
	v_mfma_f32_16x16x32_bf16 v[80:83], v[188:191], v[214:217], v[80:83]
	v_mfma_f32_16x16x32_bf16 v[68:71], v[180:183], v[222:225], v[68:71]
	v_mfma_f32_16x16x32_bf16 v[64:67], v[188:191], v[222:225], v[64:67]
	s_setprio 0
	s_barrier
	s_add_i32 s42, s68, s46
	v_lshl_add_u64 v[226:227], v[226:227], 0, s[18:19]
	s_mov_b32 m0, s42
	ds_read_b128 v[192:195], v178 offset:49152
	ds_read_b128 v[196:199], v178 offset:50176
	ds_read_b128 v[200:203], v178 offset:51200
	ds_read_b128 v[204:207], v178 offset:52224
	ds_read_b128 v[208:211], v178 offset:53248
	ds_read_b128 v[214:217], v178 offset:54272
	ds_read_b128 v[218:221], v178 offset:55296
	ds_read_b128 v[222:225], v178 offset:56320
	global_load_lds_dwordx4 v[226:227], off
	s_add_i32 m0, s42, 0x2000
	s_add_u32 s40, s40, 0x80080
	v_lshl_add_u64 v[226:227], v[228:229], 0, s[18:19]
	s_addc_u32 s41, s41, 0
	s_add_i32 s42, s69, s46
	global_load_lds_dwordx4 v[226:227], off
	v_lshl_add_u64 v[226:227], s[40:41], 0, v[142:143]
	s_mov_b32 m0, s42
	s_nop 0
	global_load_lds_dwordx4 v[226:227], off
	v_lshl_add_u64 v[226:227], s[40:41], 0, v[146:147]
	s_add_i32 m0, s42, 0x2000
	s_nop 0
	global_load_lds_dwordx4 v[226:227], off
	v_lshl_add_u64 v[226:227], v[230:231], 0, s[18:19]
	s_mov_b32 m0, s52
	s_nop 0
	global_load_lds_dwordx4 v[226:227], off
	v_lshl_add_u64 v[226:227], v[232:233], 0, s[18:19]
	s_mov_b32 m0, s53
	s_nop 0
	global_load_lds_dwordx4 v[226:227], off
	s_waitcnt vmcnt(8)
	s_waitcnt lgkmcnt(0)
	s_barrier
	s_setprio 1
	s_waitcnt lgkmcnt(0)
	v_mfma_f32_16x16x32_bf16 v[60:63], v[128:131], v[192:195], v[60:63]
	v_mfma_f32_16x16x32_bf16 v[56:59], v[136:139], v[192:195], v[56:59]
	v_mfma_f32_16x16x32_bf16 v[44:47], v[128:131], v[200:203], v[44:47]
	v_mfma_f32_16x16x32_bf16 v[40:43], v[136:139], v[200:203], v[40:43]
	v_mfma_f32_16x16x32_bf16 v[28:31], v[128:131], v[208:211], v[28:31]
	v_mfma_f32_16x16x32_bf16 v[24:27], v[136:139], v[208:211], v[24:27]
	v_mfma_f32_16x16x32_bf16 v[12:15], v[128:131], v[218:221], v[12:15]
	v_mfma_f32_16x16x32_bf16 v[8:11], v[136:139], v[218:221], v[8:11]
	v_mfma_f32_16x16x32_bf16 v[60:63], v[132:135], v[196:199], v[60:63]
	v_mfma_f32_16x16x32_bf16 v[56:59], v[158:161], v[196:199], v[56:59]
	v_mfma_f32_16x16x32_bf16 v[44:47], v[132:135], v[204:207], v[44:47]
	v_mfma_f32_16x16x32_bf16 v[40:43], v[158:161], v[204:207], v[40:43]
	v_mfma_f32_16x16x32_bf16 v[28:31], v[132:135], v[214:217], v[28:31]
	v_mfma_f32_16x16x32_bf16 v[24:27], v[158:161], v[214:217], v[24:27]
	v_mfma_f32_16x16x32_bf16 v[12:15], v[132:135], v[222:225], v[12:15]
	v_mfma_f32_16x16x32_bf16 v[8:11], v[158:161], v[222:225], v[8:11]
	s_setprio 0
	s_setprio 1
	v_mfma_f32_16x16x32_bf16 v[52:55], v[162:165], v[192:195], v[52:55]
	v_mfma_f32_16x16x32_bf16 v[48:51], v[184:187], v[192:195], v[48:51]
	v_mfma_f32_16x16x32_bf16 v[36:39], v[162:165], v[200:203], v[36:39]
	v_mfma_f32_16x16x32_bf16 v[32:35], v[184:187], v[200:203], v[32:35]
	v_mfma_f32_16x16x32_bf16 v[20:23], v[162:165], v[208:211], v[20:23]
	v_mfma_f32_16x16x32_bf16 v[16:19], v[184:187], v[208:211], v[16:19]
	v_mfma_f32_16x16x32_bf16 v[4:7], v[162:165], v[218:221], v[4:7]
	v_mfma_f32_16x16x32_bf16 v[0:3], v[184:187], v[218:221], v[0:3]
	v_mfma_f32_16x16x32_bf16 v[52:55], v[180:183], v[196:199], v[52:55]
	v_mfma_f32_16x16x32_bf16 v[48:51], v[188:191], v[196:199], v[48:51]
	v_mfma_f32_16x16x32_bf16 v[36:39], v[180:183], v[204:207], v[36:39]
	v_mfma_f32_16x16x32_bf16 v[32:35], v[188:191], v[204:207], v[32:35]
	v_mfma_f32_16x16x32_bf16 v[20:23], v[180:183], v[214:217], v[20:23]
	v_mfma_f32_16x16x32_bf16 v[16:19], v[188:191], v[214:217], v[16:19]
	v_mfma_f32_16x16x32_bf16 v[4:7], v[180:183], v[222:225], v[4:7]
	v_mfma_f32_16x16x32_bf16 v[0:3], v[188:191], v[222:225], v[0:3]
	s_setprio 0
	s_barrier
	s_add_i32 s67, s67, 2
	s_add_u32 s38, s38, 0x100
	s_addc_u32 s39, s39, 0
	s_add_u32 s64, s64, 0x100
	s_addc_u32 s65, s65, 0
	s_cmp_gt_u32 s67, 29

.LBB0_505:
	s_ashr_i32 s41, s40, 31
	s_lshl_b64 s[0:1], s[40:41], 20
	s_add_u32 s42, s14, s0
	s_addc_u32 s43, s15, s1
	s_and_b64 s[0:1], s[6:7], exec
	s_cselect_b32 s9, s43, s47
	s_cselect_b32 s41, s42, s46
	s_ashr_i32 s39, s38, 31
	s_lshl_b64 s[0:1], s[38:39], 20
	s_add_u32 s44, s35, s0
	s_addc_u32 s45, s37, s1
	s_and_b64 s[0:1], s[6:7], exec
	s_cselect_b32 s39, s45, s13
	s_cselect_b32 s67, s44, s12
	s_add_u32 s0, s46, 0x80080
	s_addc_u32 s1, s47, 0
	s_add_u32 s68, s12, 0x100
	s_addc_u32 s69, s13, 0
	s_mov_b32 s70, -2
	ds_read_b128 v[146:149], v183
	ds_read_b128 v[150:153], v183 offset:1024
	ds_read_b128 v[154:157], v183 offset:2048
	ds_read_b128 v[158:161], v183 offset:3072
	ds_read_b128 v[162:165], v184
	ds_read_b128 v[166:169], v184 offset:1024
	ds_read_b128 v[186:189], v184 offset:2048
	ds_read_b128 v[190:193], v184 offset:3072
	s_add_u32 s12, s0, 0xfff80080
	s_addc_u32 s13, s1, -1
	s_cmp_eq_u32 s70, 28
	s_cselect_b32 s47, s9, s13
	s_cselect_b32 s46, s41, s12
	s_cselect_b32 s13, s39, s69
	s_cselect_b32 s12, s67, s68
	v_lshl_add_u64 v[170:171], s[0:1], 0, v[138:139]
	s_add_i32 m0, s50, 0xc000
	ds_read_b128 v[194:197], v185
	ds_read_b128 v[198:201], v185 offset:1024
	ds_read_b128 v[202:205], v185 offset:2048
	ds_read_b128 v[206:209], v185 offset:3072
	ds_read_b128 v[214:217], v185 offset:4096
	ds_read_b128 v[218:221], v185 offset:5120
	ds_read_b128 v[222:225], v185 offset:6144
	ds_read_b128 v[226:229], v185 offset:7168
	global_load_lds_dwordx4 v[170:171], off
	v_lshl_add_u64 v[170:171], s[0:1], 0, v[140:141]
	s_add_i32 m0, s50, 0xe000
	s_nop 0
	global_load_lds_dwordx4 v[170:171], off
	s_waitcnt vmcnt(8)
	s_waitcnt lgkmcnt(0)
	s_barrier
	s_setprio 1
	s_waitcnt lgkmcnt(0)
	v_mfma_f32_16x16x32_bf16 v[124:127], v[146:149], v[194:197], 0
	v_mfma_f32_16x16x32_bf16 v[120:123], v[154:157], v[194:197], 0
	v_mfma_f32_16x16x32_bf16 v[108:111], v[146:149], v[202:205], 0
	v_mfma_f32_16x16x32_bf16 v[104:107], v[154:157], v[202:205], 0
	v_mfma_f32_16x16x32_bf16 v[92:95], v[146:149], v[214:217], 0
	v_mfma_f32_16x16x32_bf16 v[88:91], v[154:157], v[214:217], 0
	v_mfma_f32_16x16x32_bf16 v[76:79], v[146:149], v[222:225], 0
	v_mfma_f32_16x16x32_bf16 v[72:75], v[154:157], v[222:225], 0
	v_mfma_f32_16x16x32_bf16 v[124:127], v[150:153], v[198:201], v[124:127]
	v_mfma_f32_16x16x32_bf16 v[120:123], v[158:161], v[198:201], v[120:123]
	v_mfma_f32_16x16x32_bf16 v[108:111], v[150:153], v[206:209], v[108:111]
	v_mfma_f32_16x16x32_bf16 v[104:107], v[158:161], v[206:209], v[104:107]
	v_mfma_f32_16x16x32_bf16 v[92:95], v[150:153], v[218:221], v[92:95]
	v_mfma_f32_16x16x32_bf16 v[88:91], v[158:161], v[218:221], v[88:91]
	v_mfma_f32_16x16x32_bf16 v[76:79], v[150:153], v[226:229], v[76:79]
	v_mfma_f32_16x16x32_bf16 v[72:75], v[158:161], v[226:229], v[72:75]
	s_setprio 0
	s_setprio 1
	v_mfma_f32_16x16x32_bf16 v[116:119], v[162:165], v[194:197], 0
	v_mfma_f32_16x16x32_bf16 v[112:115], v[186:189], v[194:197], 0
	v_mfma_f32_16x16x32_bf16 v[100:103], v[162:165], v[202:205], 0
	v_mfma_f32_16x16x32_bf16 v[96:99], v[186:189], v[202:205], 0
	v_mfma_f32_16x16x32_bf16 v[84:87], v[162:165], v[214:217], 0
	v_mfma_f32_16x16x32_bf16 v[80:83], v[186:189], v[214:217], 0
	v_mfma_f32_16x16x32_bf16 v[68:71], v[162:165], v[222:225], 0
	v_mfma_f32_16x16x32_bf16 v[64:67], v[186:189], v[222:225], 0
	v_mfma_f32_16x16x32_bf16 v[116:119], v[166:169], v[198:201], v[116:119]
	v_mfma_f32_16x16x32_bf16 v[112:115], v[190:193], v[198:201], v[112:115]
	v_mfma_f32_16x16x32_bf16 v[100:103], v[166:169], v[206:209], v[100:103]
	v_mfma_f32_16x16x32_bf16 v[96:99], v[190:193], v[206:209], v[96:99]
	v_mfma_f32_16x16x32_bf16 v[84:87], v[166:169], v[218:221], v[84:87]
	v_mfma_f32_16x16x32_bf16 v[80:83], v[190:193], v[218:221], v[80:83]
	v_mfma_f32_16x16x32_bf16 v[68:71], v[166:169], v[226:229], v[68:71]
	v_mfma_f32_16x16x32_bf16 v[64:67], v[190:193], v[226:229], v[64:67]
	s_setprio 0
	s_barrier
	s_add_i32 s71, s58, s48
	v_lshl_add_u64 v[170:171], s[12:13], 0, v[132:133]
	s_mov_b32 m0, s71
	ds_read_b128 v[194:197], v185 offset:16384
	ds_read_b128 v[198:201], v185 offset:17408
	ds_read_b128 v[202:205], v185 offset:18432
	ds_read_b128 v[206:209], v185 offset:19456
	ds_read_b128 v[214:217], v185 offset:20480
	ds_read_b128 v[218:221], v185 offset:21504
	ds_read_b128 v[222:225], v185 offset:22528
	ds_read_b128 v[226:229], v185 offset:23552
	global_load_lds_dwordx4 v[170:171], off
	s_add_i32 m0, s71, 0x2000
	s_add_u32 s72, s12, 0x80000
	v_lshl_add_u64 v[210:211], s[12:13], 0, v[128:129]
	s_addc_u32 s73, s13, 0
	s_add_i32 s71, s59, s48
	global_load_lds_dwordx4 v[210:211], off
	v_lshl_add_u64 v[230:231], s[72:73], 0, v[132:133]
	s_mov_b32 m0, s71
	v_lshl_add_u64 v[232:233], s[46:47], 0, v[130:131]
	global_load_lds_dwordx4 v[230:231], off
	v_lshl_add_u64 v[230:231], s[72:73], 0, v[128:129]
	s_add_i32 m0, s71, 0x2000
	s_nop 0
	global_load_lds_dwordx4 v[230:231], off
	v_lshl_add_u64 v[230:231], s[46:47], 0, v[134:135]
	s_mov_b32 m0, s50
	s_nop 0
	global_load_lds_dwordx4 v[230:231], off
	s_mov_b32 m0, s51
	s_nop 0
	global_load_lds_dwordx4 v[232:233], off
	s_waitcnt vmcnt(8)
	s_waitcnt lgkmcnt(0)
	s_barrier
	s_setprio 1
	s_waitcnt lgkmcnt(0)
	v_mfma_f32_16x16x32_bf16 v[60:63], v[146:149], v[194:197], 0
	v_mfma_f32_16x16x32_bf16 v[56:59], v[154:157], v[194:197], 0
	v_mfma_f32_16x16x32_bf16 v[44:47], v[146:149], v[202:205], 0
	v_mfma_f32_16x16x32_bf16 v[40:43], v[154:157], v[202:205], 0
	v_mfma_f32_16x16x32_bf16 v[28:31], v[146:149], v[214:217], 0
	v_mfma_f32_16x16x32_bf16 v[24:27], v[154:157], v[214:217], 0
	v_mfma_f32_16x16x32_bf16 v[12:15], v[146:149], v[222:225], 0
	v_mfma_f32_16x16x32_bf16 v[8:11], v[154:157], v[222:225], 0
	v_mfma_f32_16x16x32_bf16 v[60:63], v[150:153], v[198:201], v[60:63]
	v_mfma_f32_16x16x32_bf16 v[56:59], v[158:161], v[198:201], v[56:59]
	v_mfma_f32_16x16x32_bf16 v[44:47], v[150:153], v[206:209], v[44:47]
	v_mfma_f32_16x16x32_bf16 v[40:43], v[158:161], v[206:209], v[40:43]
	v_mfma_f32_16x16x32_bf16 v[28:31], v[150:153], v[218:221], v[28:31]
	v_mfma_f32_16x16x32_bf16 v[24:27], v[158:161], v[218:221], v[24:27]
	v_mfma_f32_16x16x32_bf16 v[12:15], v[150:153], v[226:229], v[12:15]
	v_mfma_f32_16x16x32_bf16 v[8:11], v[158:161], v[226:229], v[8:11]
	s_setprio 0
	s_setprio 1
	v_mfma_f32_16x16x32_bf16 v[52:55], v[162:165], v[194:197], 0
	v_mfma_f32_16x16x32_bf16 v[48:51], v[186:189], v[194:197], 0
	v_mfma_f32_16x16x32_bf16 v[36:39], v[162:165], v[202:205], 0
	v_mfma_f32_16x16x32_bf16 v[32:35], v[186:189], v[202:205], 0
	v_mfma_f32_16x16x32_bf16 v[20:23], v[162:165], v[214:217], 0
	v_mfma_f32_16x16x32_bf16 v[16:19], v[186:189], v[214:217], 0
	v_mfma_f32_16x16x32_bf16 v[4:7], v[162:165], v[222:225], 0
	v_mfma_f32_16x16x32_bf16 v[0:3], v[186:189], v[222:225], 0
	v_mfma_f32_16x16x32_bf16 v[52:55], v[166:169], v[198:201], v[52:55]
	v_mfma_f32_16x16x32_bf16 v[48:51], v[190:193], v[198:201], v[48:51]
	v_mfma_f32_16x16x32_bf16 v[36:39], v[166:169], v[206:209], v[36:39]
	v_mfma_f32_16x16x32_bf16 v[32:35], v[190:193], v[206:209], v[32:35]
	v_mfma_f32_16x16x32_bf16 v[20:23], v[166:169], v[218:221], v[20:23]
	v_mfma_f32_16x16x32_bf16 v[16:19], v[190:193], v[218:221], v[16:19]
	v_mfma_f32_16x16x32_bf16 v[4:7], v[166:169], v[226:229], v[4:7]
	v_mfma_f32_16x16x32_bf16 v[0:3], v[190:193], v[226:229], v[0:3]
	s_setprio 0
	s_barrier
	s_add_i32 s71, 0, 0x18000
	s_add_i32 s72, 0, 0x1c000
	v_add_u32_e32 v158, s71, v178
	v_add_u32_e32 v190, s72, v178
	ds_read_b128 v[146:149], v158
	ds_read_b128 v[150:153], v158 offset:1024
	ds_read_b128 v[154:157], v158 offset:2048
	ds_read_b128 v[158:161], v158 offset:3072
	ds_read_b128 v[162:165], v190
	ds_read_b128 v[166:169], v190 offset:1024
	ds_read_b128 v[186:189], v190 offset:2048
	ds_read_b128 v[190:193], v190 offset:3072
	s_add_u32 s46, s46, 0x80000
	s_addc_u32 s47, s47, 0
	s_mov_b32 m0, s52
	v_lshl_add_u64 v[234:235], s[46:47], 0, v[134:135]
	ds_read_b128 v[194:197], v185 offset:32768
	ds_read_b128 v[198:201], v185 offset:33792
	ds_read_b128 v[202:205], v185 offset:34816
	ds_read_b128 v[206:209], v185 offset:35840
	ds_read_b128 v[214:217], v185 offset:36864
	ds_read_b128 v[218:221], v185 offset:37888
	ds_read_b128 v[222:225], v185 offset:38912
	ds_read_b128 v[226:229], v185 offset:39936
	global_load_lds_dwordx4 v[234:235], off
	v_lshl_add_u64 v[234:235], s[46:47], 0, v[130:131]
	s_mov_b32 m0, s53
	s_nop 0
	global_load_lds_dwordx4 v[234:235], off
	s_waitcnt vmcnt(8)
	s_waitcnt lgkmcnt(0)
	s_barrier
	s_setprio 1
	s_waitcnt lgkmcnt(0)
	v_mfma_f32_16x16x32_bf16 v[124:127], v[146:149], v[194:197], v[124:127]
	v_mfma_f32_16x16x32_bf16 v[120:123], v[154:157], v[194:197], v[120:123]
	v_mfma_f32_16x16x32_bf16 v[108:111], v[146:149], v[202:205], v[108:111]
	v_mfma_f32_16x16x32_bf16 v[104:107], v[154:157], v[202:205], v[104:107]
	v_mfma_f32_16x16x32_bf16 v[92:95], v[146:149], v[214:217], v[92:95]
	v_mfma_f32_16x16x32_bf16 v[88:91], v[154:157], v[214:217], v[88:91]
	v_mfma_f32_16x16x32_bf16 v[76:79], v[146:149], v[222:225], v[76:79]
	v_mfma_f32_16x16x32_bf16 v[72:75], v[154:157], v[222:225], v[72:75]
	v_mfma_f32_16x16x32_bf16 v[124:127], v[150:153], v[198:201], v[124:127]
	v_mfma_f32_16x16x32_bf16 v[120:123], v[158:161], v[198:201], v[120:123]
	v_mfma_f32_16x16x32_bf16 v[108:111], v[150:153], v[206:209], v[108:111]
	v_mfma_f32_16x16x32_bf16 v[104:107], v[158:161], v[206:209], v[104:107]
	v_mfma_f32_16x16x32_bf16 v[92:95], v[150:153], v[218:221], v[92:95]
	v_mfma_f32_16x16x32_bf16 v[88:91], v[158:161], v[218:221], v[88:91]
	v_mfma_f32_16x16x32_bf16 v[76:79], v[150:153], v[226:229], v[76:79]
	v_mfma_f32_16x16x32_bf16 v[72:75], v[158:161], v[226:229], v[72:75]
	s_setprio 0
	s_setprio 1
	v_mfma_f32_16x16x32_bf16 v[116:119], v[162:165], v[194:197], v[116:119]
	v_mfma_f32_16x16x32_bf16 v[112:115], v[186:189], v[194:197], v[112:115]
	v_mfma_f32_16x16x32_bf16 v[100:103], v[162:165], v[202:205], v[100:103]
	v_mfma_f32_16x16x32_bf16 v[96:99], v[186:189], v[202:205], v[96:99]
	v_mfma_f32_16x16x32_bf16 v[84:87], v[162:165], v[214:217], v[84:87]
	v_mfma_f32_16x16x32_bf16 v[80:83], v[186:189], v[214:217], v[80:83]
	v_mfma_f32_16x16x32_bf16 v[68:71], v[162:165], v[222:225], v[68:71]
	v_mfma_f32_16x16x32_bf16 v[64:67], v[186:189], v[222:225], v[64:67]
	v_mfma_f32_16x16x32_bf16 v[116:119], v[166:169], v[198:201], v[116:119]
	v_mfma_f32_16x16x32_bf16 v[112:115], v[190:193], v[198:201], v[112:115]
	v_mfma_f32_16x16x32_bf16 v[100:103], v[166:169], v[206:209], v[100:103]
	v_mfma_f32_16x16x32_bf16 v[96:99], v[190:193], v[206:209], v[96:99]
	v_mfma_f32_16x16x32_bf16 v[84:87], v[166:169], v[218:221], v[84:87]
	v_mfma_f32_16x16x32_bf16 v[80:83], v[190:193], v[218:221], v[80:83]
	v_mfma_f32_16x16x32_bf16 v[68:71], v[166:169], v[226:229], v[68:71]
	v_mfma_f32_16x16x32_bf16 v[64:67], v[190:193], v[226:229], v[64:67]
	s_setprio 0
	s_barrier
	s_add_i32 s46, s71, s48
	v_lshl_add_u64 v[170:171], v[170:171], 0, s[22:23]
	s_mov_b32 m0, s46
	ds_read_b128 v[194:197], v185 offset:49152
	ds_read_b128 v[198:201], v185 offset:50176
	ds_read_b128 v[202:205], v185 offset:51200
	ds_read_b128 v[206:209], v185 offset:52224
	ds_read_b128 v[214:217], v185 offset:53248
	ds_read_b128 v[218:221], v185 offset:54272
	ds_read_b128 v[222:225], v185 offset:55296
	ds_read_b128 v[226:229], v185 offset:56320
	global_load_lds_dwordx4 v[170:171], off
	s_add_i32 m0, s46, 0x2000
	s_add_u32 s12, s12, 0x80080
	v_lshl_add_u64 v[170:171], v[210:211], 0, s[22:23]
	s_addc_u32 s13, s13, 0
	s_add_i32 s46, s72, s48
	global_load_lds_dwordx4 v[170:171], off
	v_lshl_add_u64 v[170:171], s[12:13], 0, v[132:133]
	s_mov_b32 m0, s46
	s_nop 0
	global_load_lds_dwordx4 v[170:171], off
	v_lshl_add_u64 v[170:171], s[12:13], 0, v[128:129]
	s_add_i32 m0, s46, 0x2000
	s_nop 0
	global_load_lds_dwordx4 v[170:171], off
	v_lshl_add_u64 v[170:171], v[230:231], 0, s[22:23]
	s_mov_b32 m0, s55
	s_nop 0
	global_load_lds_dwordx4 v[170:171], off
	v_lshl_add_u64 v[170:171], v[232:233], 0, s[22:23]
	s_mov_b32 m0, s56
	s_nop 0
	global_load_lds_dwordx4 v[170:171], off
	s_waitcnt vmcnt(8)
	s_waitcnt lgkmcnt(0)
	s_barrier
	s_setprio 1
	s_waitcnt lgkmcnt(0)
	v_mfma_f32_16x16x32_bf16 v[60:63], v[146:149], v[194:197], v[60:63]
	v_mfma_f32_16x16x32_bf16 v[56:59], v[154:157], v[194:197], v[56:59]
	v_mfma_f32_16x16x32_bf16 v[44:47], v[146:149], v[202:205], v[44:47]
	v_mfma_f32_16x16x32_bf16 v[40:43], v[154:157], v[202:205], v[40:43]
	v_mfma_f32_16x16x32_bf16 v[28:31], v[146:149], v[214:217], v[28:31]
	v_mfma_f32_16x16x32_bf16 v[24:27], v[154:157], v[214:217], v[24:27]
	v_mfma_f32_16x16x32_bf16 v[12:15], v[146:149], v[222:225], v[12:15]
	v_mfma_f32_16x16x32_bf16 v[8:11], v[154:157], v[222:225], v[8:11]
	v_mfma_f32_16x16x32_bf16 v[60:63], v[150:153], v[198:201], v[60:63]
	v_mfma_f32_16x16x32_bf16 v[56:59], v[158:161], v[198:201], v[56:59]
	v_mfma_f32_16x16x32_bf16 v[44:47], v[150:153], v[206:209], v[44:47]
	v_mfma_f32_16x16x32_bf16 v[40:43], v[158:161], v[206:209], v[40:43]
	v_mfma_f32_16x16x32_bf16 v[28:31], v[150:153], v[218:221], v[28:31]
	v_mfma_f32_16x16x32_bf16 v[24:27], v[158:161], v[218:221], v[24:27]
	v_mfma_f32_16x16x32_bf16 v[12:15], v[150:153], v[226:229], v[12:15]
	v_mfma_f32_16x16x32_bf16 v[8:11], v[158:161], v[226:229], v[8:11]
	s_setprio 0
	s_setprio 1
	v_mfma_f32_16x16x32_bf16 v[52:55], v[162:165], v[194:197], v[52:55]
	v_mfma_f32_16x16x32_bf16 v[48:51], v[186:189], v[194:197], v[48:51]
	v_mfma_f32_16x16x32_bf16 v[36:39], v[162:165], v[202:205], v[36:39]
	v_mfma_f32_16x16x32_bf16 v[32:35], v[186:189], v[202:205], v[32:35]
	v_mfma_f32_16x16x32_bf16 v[20:23], v[162:165], v[214:217], v[20:23]
	v_mfma_f32_16x16x32_bf16 v[16:19], v[186:189], v[214:217], v[16:19]
	v_mfma_f32_16x16x32_bf16 v[4:7], v[162:165], v[222:225], v[4:7]
	v_mfma_f32_16x16x32_bf16 v[0:3], v[186:189], v[222:225], v[0:3]
	v_mfma_f32_16x16x32_bf16 v[52:55], v[166:169], v[198:201], v[52:55]
	v_mfma_f32_16x16x32_bf16 v[48:51], v[190:193], v[198:201], v[48:51]
	v_mfma_f32_16x16x32_bf16 v[36:39], v[166:169], v[206:209], v[36:39]
	v_mfma_f32_16x16x32_bf16 v[32:35], v[190:193], v[206:209], v[32:35]
	v_mfma_f32_16x16x32_bf16 v[20:23], v[166:169], v[218:221], v[20:23]
	v_mfma_f32_16x16x32_bf16 v[16:19], v[190:193], v[218:221], v[16:19]
	v_mfma_f32_16x16x32_bf16 v[4:7], v[166:169], v[226:229], v[4:7]
	v_mfma_f32_16x16x32_bf16 v[0:3], v[190:193], v[226:229], v[0:3]
	s_setprio 0
	s_barrier
	s_add_i32 s70, s70, 2
	s_add_u32 s0, s0, 0x100
	s_addc_u32 s1, s1, 0
	s_add_u32 s68, s68, 0x100
	s_addc_u32 s69, s69, 0
	s_cmp_gt_u32 s70, 29

.LBB0_549:
	s_add_u32 s58, s34, 0x100
	s_addc_u32 s59, s35, 0
	s_mov_b32 s63, -2
	ds_read_b128 v[144:147], v155
	ds_read_b128 v[148:151], v155 offset:1024
	ds_read_b128 v[158:161], v155 offset:2048
	ds_read_b128 v[162:165], v155 offset:3072
	ds_read_b128 v[166:169], v156
	ds_read_b128 v[178:181], v156 offset:1024
	ds_read_b128 v[182:185], v156 offset:2048
	ds_read_b128 v[186:189], v156 offset:3072
	s_add_u32 s34, s26, 0x100
	s_addc_u32 s35, s27, 0
	s_cmpk_eq_i32 s63, 0x54
	s_cselect_b32 s39, s1, s35
	s_cselect_b32 s38, s0, s34
	s_cselect_b32 s37, s7, s59
	s_cselect_b32 s36, s6, s58
	v_lshl_add_u64 v[170:171], s[26:27], 0, v[136:137]
	s_add_i32 m0, s44, 0xc000
	ds_read_b128 v[190:193], v157
	ds_read_b128 v[194:197], v157 offset:1024
	ds_read_b128 v[198:201], v157 offset:2048
	ds_read_b128 v[202:205], v157 offset:3072
	ds_read_b128 v[206:209], v157 offset:4096
	ds_read_b128 v[214:217], v157 offset:5120
	ds_read_b128 v[218:221], v157 offset:6144
	ds_read_b128 v[222:225], v157 offset:7168
	global_load_lds_dwordx4 v[170:171], off
	v_lshl_add_u64 v[170:171], s[26:27], 0, v[138:139]
	s_add_i32 m0, s44, 0xe000
	s_nop 0
	global_load_lds_dwordx4 v[170:171], off
	s_waitcnt vmcnt(8)
	s_waitcnt lgkmcnt(0)
	s_barrier
	s_setprio 1
	s_waitcnt lgkmcnt(0)
	v_mfma_f32_16x16x32_bf16 v[124:127], v[144:147], v[190:193], 0
	v_mfma_f32_16x16x32_bf16 v[120:123], v[158:161], v[190:193], 0
	v_mfma_f32_16x16x32_bf16 v[116:119], v[144:147], v[198:201], 0
	v_mfma_f32_16x16x32_bf16 v[112:115], v[158:161], v[198:201], 0
	v_mfma_f32_16x16x32_bf16 v[92:95], v[144:147], v[206:209], 0
	v_mfma_f32_16x16x32_bf16 v[88:91], v[158:161], v[206:209], 0
	v_mfma_f32_16x16x32_bf16 v[84:87], v[144:147], v[218:221], 0
	v_mfma_f32_16x16x32_bf16 v[80:83], v[158:161], v[218:221], 0
	v_mfma_f32_16x16x32_bf16 v[124:127], v[148:151], v[194:197], v[124:127]
	v_mfma_f32_16x16x32_bf16 v[120:123], v[162:165], v[194:197], v[120:123]
	v_mfma_f32_16x16x32_bf16 v[116:119], v[148:151], v[202:205], v[116:119]
	v_mfma_f32_16x16x32_bf16 v[112:115], v[162:165], v[202:205], v[112:115]
	v_mfma_f32_16x16x32_bf16 v[92:95], v[148:151], v[214:217], v[92:95]
	v_mfma_f32_16x16x32_bf16 v[88:91], v[162:165], v[214:217], v[88:91]
	v_mfma_f32_16x16x32_bf16 v[84:87], v[148:151], v[222:225], v[84:87]
	v_mfma_f32_16x16x32_bf16 v[80:83], v[162:165], v[222:225], v[80:83]
	s_setprio 0
	s_setprio 1
	v_mfma_f32_16x16x32_bf16 v[108:111], v[166:169], v[190:193], 0
	v_mfma_f32_16x16x32_bf16 v[104:107], v[182:185], v[190:193], 0
	v_mfma_f32_16x16x32_bf16 v[100:103], v[166:169], v[198:201], 0
	v_mfma_f32_16x16x32_bf16 v[96:99], v[182:185], v[198:201], 0
	v_mfma_f32_16x16x32_bf16 v[76:79], v[166:169], v[206:209], 0
	v_mfma_f32_16x16x32_bf16 v[72:75], v[182:185], v[206:209], 0
	v_mfma_f32_16x16x32_bf16 v[68:71], v[166:169], v[218:221], 0
	v_mfma_f32_16x16x32_bf16 v[64:67], v[182:185], v[218:221], 0
	v_mfma_f32_16x16x32_bf16 v[108:111], v[178:181], v[194:197], v[108:111]
	v_mfma_f32_16x16x32_bf16 v[104:107], v[186:189], v[194:197], v[104:107]
	v_mfma_f32_16x16x32_bf16 v[100:103], v[178:181], v[202:205], v[100:103]
	v_mfma_f32_16x16x32_bf16 v[96:99], v[186:189], v[202:205], v[96:99]
	v_mfma_f32_16x16x32_bf16 v[76:79], v[178:181], v[214:217], v[76:79]
	v_mfma_f32_16x16x32_bf16 v[72:75], v[186:189], v[214:217], v[72:75]
	v_mfma_f32_16x16x32_bf16 v[68:71], v[178:181], v[222:225], v[68:71]
	v_mfma_f32_16x16x32_bf16 v[64:67], v[186:189], v[222:225], v[64:67]
	s_setprio 0
	s_barrier
	s_add_i32 s26, s52, s43
	v_lshl_add_u64 v[170:171], s[36:37], 0, v[130:131]
	s_mov_b32 m0, s26
	ds_read_b128 v[190:193], v157 offset:16384
	ds_read_b128 v[194:197], v157 offset:17408
	ds_read_b128 v[198:201], v157 offset:18432
	ds_read_b128 v[202:205], v157 offset:19456
	ds_read_b128 v[206:209], v157 offset:20480
	ds_read_b128 v[214:217], v157 offset:21504
	ds_read_b128 v[218:221], v157 offset:22528
	ds_read_b128 v[222:225], v157 offset:23552
	global_load_lds_dwordx4 v[170:171], off
	s_add_i32 m0, s26, 0x2000
	s_add_u32 s26, s36, 0x160000
	v_lshl_add_u64 v[210:211], s[36:37], 0, v[134:135]
	s_addc_u32 s27, s37, 0
	s_add_i32 s64, s53, s43
	global_load_lds_dwordx4 v[210:211], off
	v_lshl_add_u64 v[226:227], s[26:27], 0, v[130:131]
	s_mov_b32 m0, s64
	v_lshl_add_u64 v[228:229], s[38:39], 0, v[132:133]
	global_load_lds_dwordx4 v[226:227], off
	v_lshl_add_u64 v[226:227], s[26:27], 0, v[134:135]
	s_add_i32 m0, s64, 0x2000
	s_nop 0
	global_load_lds_dwordx4 v[226:227], off
	v_lshl_add_u64 v[226:227], s[38:39], 0, v[128:129]
	s_mov_b32 m0, s44
	s_nop 0
	global_load_lds_dwordx4 v[226:227], off
	s_mov_b32 m0, s45
	s_nop 0
	global_load_lds_dwordx4 v[228:229], off
	s_waitcnt vmcnt(8)
	s_waitcnt lgkmcnt(0)
	s_barrier
	s_setprio 1
	s_waitcnt lgkmcnt(0)
	v_mfma_f32_16x16x32_bf16 v[60:63], v[144:147], v[190:193], 0
	v_mfma_f32_16x16x32_bf16 v[56:59], v[158:161], v[190:193], 0
	v_mfma_f32_16x16x32_bf16 v[52:55], v[144:147], v[198:201], 0
	v_mfma_f32_16x16x32_bf16 v[48:51], v[158:161], v[198:201], 0
	v_mfma_f32_16x16x32_bf16 v[28:31], v[144:147], v[206:209], 0
	v_mfma_f32_16x16x32_bf16 v[24:27], v[158:161], v[206:209], 0
	v_mfma_f32_16x16x32_bf16 v[16:19], v[144:147], v[218:221], 0
	v_mfma_f32_16x16x32_bf16 v[8:11], v[158:161], v[218:221], 0
	v_mfma_f32_16x16x32_bf16 v[60:63], v[148:151], v[194:197], v[60:63]
	v_mfma_f32_16x16x32_bf16 v[56:59], v[162:165], v[194:197], v[56:59]
	v_mfma_f32_16x16x32_bf16 v[52:55], v[148:151], v[202:205], v[52:55]
	v_mfma_f32_16x16x32_bf16 v[48:51], v[162:165], v[202:205], v[48:51]
	v_mfma_f32_16x16x32_bf16 v[28:31], v[148:151], v[214:217], v[28:31]
	v_mfma_f32_16x16x32_bf16 v[24:27], v[162:165], v[214:217], v[24:27]
	v_mfma_f32_16x16x32_bf16 v[16:19], v[148:151], v[222:225], v[16:19]
	v_mfma_f32_16x16x32_bf16 v[8:11], v[162:165], v[222:225], v[8:11]
	s_setprio 0
	s_setprio 1
	v_mfma_f32_16x16x32_bf16 v[44:47], v[166:169], v[190:193], 0
	v_mfma_f32_16x16x32_bf16 v[40:43], v[182:185], v[190:193], 0
	v_mfma_f32_16x16x32_bf16 v[36:39], v[166:169], v[198:201], 0
	v_mfma_f32_16x16x32_bf16 v[32:35], v[182:185], v[198:201], 0
	v_mfma_f32_16x16x32_bf16 v[20:23], v[166:169], v[206:209], 0
	v_mfma_f32_16x16x32_bf16 v[12:15], v[182:185], v[206:209], 0
	v_mfma_f32_16x16x32_bf16 v[4:7], v[166:169], v[218:221], 0
	v_mfma_f32_16x16x32_bf16 v[0:3], v[182:185], v[218:221], 0
	v_mfma_f32_16x16x32_bf16 v[44:47], v[178:181], v[194:197], v[44:47]
	v_mfma_f32_16x16x32_bf16 v[40:43], v[186:189], v[194:197], v[40:43]
	v_mfma_f32_16x16x32_bf16 v[36:39], v[178:181], v[202:205], v[36:39]
	v_mfma_f32_16x16x32_bf16 v[32:35], v[186:189], v[202:205], v[32:35]
	v_mfma_f32_16x16x32_bf16 v[20:23], v[178:181], v[214:217], v[20:23]
	v_mfma_f32_16x16x32_bf16 v[12:15], v[186:189], v[214:217], v[12:15]
	v_mfma_f32_16x16x32_bf16 v[4:7], v[178:181], v[222:225], v[4:7]
	v_mfma_f32_16x16x32_bf16 v[0:3], v[186:189], v[222:225], v[0:3]
	s_setprio 0
	s_barrier
	s_add_i32 s64, 0, 0x18000
	s_add_i32 s65, 0, 0x1c000
	v_add_u32_e32 v162, s64, v153
	v_add_u32_e32 v177, s65, v153
	ds_read_b128 v[144:147], v162
	ds_read_b128 v[148:151], v162 offset:1024
	ds_read_b128 v[158:161], v162 offset:2048
	ds_read_b128 v[162:165], v162 offset:3072
	ds_read_b128 v[166:169], v177
	ds_read_b128 v[178:181], v177 offset:1024
	ds_read_b128 v[182:185], v177 offset:2048
	ds_read_b128 v[186:189], v177 offset:3072
	s_add_u32 s26, s38, 0x160000
	s_addc_u32 s27, s39, 0
	s_mov_b32 m0, s46
	v_lshl_add_u64 v[230:231], s[26:27], 0, v[128:129]
	ds_read_b128 v[190:193], v157 offset:32768
	ds_read_b128 v[194:197], v157 offset:33792
	ds_read_b128 v[198:201], v157 offset:34816
	ds_read_b128 v[202:205], v157 offset:35840
	ds_read_b128 v[206:209], v157 offset:36864
	ds_read_b128 v[214:217], v157 offset:37888
	ds_read_b128 v[218:221], v157 offset:38912
	ds_read_b128 v[222:225], v157 offset:39936
	global_load_lds_dwordx4 v[230:231], off
	v_lshl_add_u64 v[230:231], s[26:27], 0, v[132:133]
	s_mov_b32 m0, s47
	s_nop 0
	global_load_lds_dwordx4 v[230:231], off
	s_waitcnt vmcnt(8)
	s_waitcnt lgkmcnt(0)
	s_barrier
	s_setprio 1
	s_waitcnt lgkmcnt(0)
	v_mfma_f32_16x16x32_bf16 v[124:127], v[144:147], v[190:193], v[124:127]
	v_mfma_f32_16x16x32_bf16 v[120:123], v[158:161], v[190:193], v[120:123]
	v_mfma_f32_16x16x32_bf16 v[116:119], v[144:147], v[198:201], v[116:119]
	v_mfma_f32_16x16x32_bf16 v[112:115], v[158:161], v[198:201], v[112:115]
	v_mfma_f32_16x16x32_bf16 v[92:95], v[144:147], v[206:209], v[92:95]
	v_mfma_f32_16x16x32_bf16 v[88:91], v[158:161], v[206:209], v[88:91]
	v_mfma_f32_16x16x32_bf16 v[84:87], v[144:147], v[218:221], v[84:87]
	v_mfma_f32_16x16x32_bf16 v[80:83], v[158:161], v[218:221], v[80:83]
	v_mfma_f32_16x16x32_bf16 v[124:127], v[148:151], v[194:197], v[124:127]
	v_mfma_f32_16x16x32_bf16 v[120:123], v[162:165], v[194:197], v[120:123]
	v_mfma_f32_16x16x32_bf16 v[116:119], v[148:151], v[202:205], v[116:119]
	v_mfma_f32_16x16x32_bf16 v[112:115], v[162:165], v[202:205], v[112:115]
	v_mfma_f32_16x16x32_bf16 v[92:95], v[148:151], v[214:217], v[92:95]
	v_mfma_f32_16x16x32_bf16 v[88:91], v[162:165], v[214:217], v[88:91]
	v_mfma_f32_16x16x32_bf16 v[84:87], v[148:151], v[222:225], v[84:87]
	v_mfma_f32_16x16x32_bf16 v[80:83], v[162:165], v[222:225], v[80:83]
	s_setprio 0
	s_setprio 1
	v_mfma_f32_16x16x32_bf16 v[108:111], v[166:169], v[190:193], v[108:111]
	v_mfma_f32_16x16x32_bf16 v[104:107], v[182:185], v[190:193], v[104:107]
	v_mfma_f32_16x16x32_bf16 v[100:103], v[166:169], v[198:201], v[100:103]
	v_mfma_f32_16x16x32_bf16 v[96:99], v[182:185], v[198:201], v[96:99]
	v_mfma_f32_16x16x32_bf16 v[76:79], v[166:169], v[206:209], v[76:79]
	v_mfma_f32_16x16x32_bf16 v[72:75], v[182:185], v[206:209], v[72:75]
	v_mfma_f32_16x16x32_bf16 v[68:71], v[166:169], v[218:221], v[68:71]
	v_mfma_f32_16x16x32_bf16 v[64:67], v[182:185], v[218:221], v[64:67]
	v_mfma_f32_16x16x32_bf16 v[108:111], v[178:181], v[194:197], v[108:111]
	v_mfma_f32_16x16x32_bf16 v[104:107], v[186:189], v[194:197], v[104:107]
	v_mfma_f32_16x16x32_bf16 v[100:103], v[178:181], v[202:205], v[100:103]
	v_mfma_f32_16x16x32_bf16 v[96:99], v[186:189], v[202:205], v[96:99]
	v_mfma_f32_16x16x32_bf16 v[76:79], v[178:181], v[214:217], v[76:79]
	v_mfma_f32_16x16x32_bf16 v[72:75], v[186:189], v[214:217], v[72:75]
	v_mfma_f32_16x16x32_bf16 v[68:71], v[178:181], v[222:225], v[68:71]
	v_mfma_f32_16x16x32_bf16 v[64:67], v[186:189], v[222:225], v[64:67]
	s_setprio 0
	s_barrier
	s_add_i32 s26, s64, s43
	v_lshl_add_u64 v[170:171], v[170:171], 0, s[8:9]
	s_mov_b32 m0, s26
	ds_read_b128 v[190:193], v157 offset:49152
	ds_read_b128 v[194:197], v157 offset:50176
	ds_read_b128 v[198:201], v157 offset:51200
	ds_read_b128 v[202:205], v157 offset:52224
	ds_read_b128 v[206:209], v157 offset:53248
	ds_read_b128 v[214:217], v157 offset:54272
	ds_read_b128 v[218:221], v157 offset:55296
	ds_read_b128 v[222:225], v157 offset:56320
	global_load_lds_dwordx4 v[170:171], off
	s_add_i32 m0, s26, 0x2000
	s_add_u32 s26, s36, 0x160080
	v_lshl_add_u64 v[170:171], v[210:211], 0, s[8:9]
	s_addc_u32 s27, s37, 0
	s_add_i32 s36, s65, s43
	global_load_lds_dwordx4 v[170:171], off
	v_lshl_add_u64 v[170:171], s[26:27], 0, v[130:131]
	s_mov_b32 m0, s36
	s_nop 0
	global_load_lds_dwordx4 v[170:171], off
	v_lshl_add_u64 v[170:171], s[26:27], 0, v[134:135]
	s_add_i32 m0, s36, 0x2000
	s_nop 0
	global_load_lds_dwordx4 v[170:171], off
	v_lshl_add_u64 v[170:171], v[226:227], 0, s[8:9]
	s_mov_b32 m0, s49
	s_nop 0
	global_load_lds_dwordx4 v[170:171], off
	v_lshl_add_u64 v[170:171], v[228:229], 0, s[8:9]
	s_mov_b32 m0, s50
	s_nop 0
	global_load_lds_dwordx4 v[170:171], off
	s_waitcnt vmcnt(8)
	s_waitcnt lgkmcnt(0)
	s_barrier
	s_setprio 1
	s_waitcnt lgkmcnt(0)
	v_mfma_f32_16x16x32_bf16 v[60:63], v[144:147], v[190:193], v[60:63]
	v_mfma_f32_16x16x32_bf16 v[56:59], v[158:161], v[190:193], v[56:59]
	v_mfma_f32_16x16x32_bf16 v[52:55], v[144:147], v[198:201], v[52:55]
	v_mfma_f32_16x16x32_bf16 v[48:51], v[158:161], v[198:201], v[48:51]
	v_mfma_f32_16x16x32_bf16 v[28:31], v[144:147], v[206:209], v[28:31]
	v_mfma_f32_16x16x32_bf16 v[24:27], v[158:161], v[206:209], v[24:27]
	v_mfma_f32_16x16x32_bf16 v[16:19], v[144:147], v[218:221], v[16:19]
	v_mfma_f32_16x16x32_bf16 v[8:11], v[158:161], v[218:221], v[8:11]
	v_mfma_f32_16x16x32_bf16 v[60:63], v[148:151], v[194:197], v[60:63]
	v_mfma_f32_16x16x32_bf16 v[56:59], v[162:165], v[194:197], v[56:59]
	v_mfma_f32_16x16x32_bf16 v[52:55], v[148:151], v[202:205], v[52:55]
	v_mfma_f32_16x16x32_bf16 v[48:51], v[162:165], v[202:205], v[48:51]
	v_mfma_f32_16x16x32_bf16 v[28:31], v[148:151], v[214:217], v[28:31]
	v_mfma_f32_16x16x32_bf16 v[24:27], v[162:165], v[214:217], v[24:27]
	v_mfma_f32_16x16x32_bf16 v[16:19], v[148:151], v[222:225], v[16:19]
	v_mfma_f32_16x16x32_bf16 v[8:11], v[162:165], v[222:225], v[8:11]
	s_setprio 0
	s_setprio 1
	v_mfma_f32_16x16x32_bf16 v[44:47], v[166:169], v[190:193], v[44:47]
	v_mfma_f32_16x16x32_bf16 v[40:43], v[182:185], v[190:193], v[40:43]
	v_mfma_f32_16x16x32_bf16 v[36:39], v[166:169], v[198:201], v[36:39]
	v_mfma_f32_16x16x32_bf16 v[32:35], v[182:185], v[198:201], v[32:35]
	v_mfma_f32_16x16x32_bf16 v[20:23], v[166:169], v[206:209], v[20:23]
	v_mfma_f32_16x16x32_bf16 v[12:15], v[182:185], v[206:209], v[12:15]
	v_mfma_f32_16x16x32_bf16 v[4:7], v[166:169], v[218:221], v[4:7]
	v_mfma_f32_16x16x32_bf16 v[0:3], v[182:185], v[218:221], v[0:3]
	v_mfma_f32_16x16x32_bf16 v[44:47], v[178:181], v[194:197], v[44:47]
	v_mfma_f32_16x16x32_bf16 v[40:43], v[186:189], v[194:197], v[40:43]
	v_mfma_f32_16x16x32_bf16 v[36:39], v[178:181], v[202:205], v[36:39]
	v_mfma_f32_16x16x32_bf16 v[32:35], v[186:189], v[202:205], v[32:35]
	v_mfma_f32_16x16x32_bf16 v[20:23], v[178:181], v[214:217], v[20:23]
	v_mfma_f32_16x16x32_bf16 v[12:15], v[186:189], v[214:217], v[12:15]
	v_mfma_f32_16x16x32_bf16 v[4:7], v[178:181], v[222:225], v[4:7]
	v_mfma_f32_16x16x32_bf16 v[0:3], v[186:189], v[222:225], v[0:3]
	s_setprio 0
	s_barrier
	s_add_i32 s63, s63, 2
	s_add_u32 s58, s58, 0x100
	s_addc_u32 s59, s59, 0
	s_cmpk_gt_u32 s63, 0x55
	s_mov_b64 s[26:27], s[34:35]
